# v41 with per-segment s_setprio flips deleted and one static s_setprio 1 for the older workgroup half (waves 0-3) during GEMM phases
# speedup vs baseline: 1.0052x; 1.0052x over previous
; __global__ void __launch_bounds__(512, 2) fwd_kernel(Params p) {
;     ...
;         const int l = ph < 2 ? 0 : (ph - 2) / 8, s = ph < 2 ? 0 : (ph - 2) % 8 + 1;
;         float* ssq_all = (float*)(p.ws + WS_SSQ);
;         const float* shw_all = (const float*)(p.ws + WS_SHW);
;         if (s == 0) {
;             phase_shw(p, lds, tid); asm volatile("" : "+v"(tid)); phase_weights_a0(p, lds, tid); asm volatile("" : "+v"(tid)); phase_norm_first(p, tid);
;         }
;         else if (s == 4) phase_mixer(p, l, lds, tid);
;         else if (s == 5) phase_combine(p, l, tid);
;         else if (s == 1 || s == 7) {
;             const int sub = s == 1 ? 0 : 2;
;             pg8::EpiSwiGLU E{(bf16*)(p.ws + WS_BIG), ssq_all + (size_t)(l * 3 + sub) * T, shw_all + (size_t)(l * 3 + sub) * 24 * 5632};
;             run_gemm(lds, (const bf16*)(p.ws + (s == 1 ? WS_H : WS_H2)), (const bf16*)(p.ws + (s == 1 ? WS_WGU0 : WS_WGU1)), 2 * FF, D, E, tid);
;         } else if (s == 3) {
;             pg8::EpiProj E{(bf16*)(p.ws + WS_BIG), ssq_all + (size_t)(l * 3 + 1) * T, shw_all + (size_t)(l * 3 + 1) * 24 * 5632};
;             run_gemm(lds, (const bf16*)(p.ws + WS_H), (const bf16*)(p.ws + WS_WIN), NPJ, D, E, tid);
;         } else {
;             const int sub = s == 2 ? 0 : (s == 6 ? 1 : 2);
;             pg8::EpiRes E{p.xp, p.xs, p.out, p.ws, l, sub, ((l == 0) && s == 2) ? 1 : 0};
;             const bf16* A = (const bf16*)(p.ws + (s == 6 ? WS_H : WS_BIG));
;             const bf16* Bt = (const bf16*)(p.ws + (s == 2 ? WS_WD0 : (s == 6 ? WS_WOUT : WS_WD1)));
;             run_gemm(lds, A, Bt, D, s == 6 ? D : FF, E, tid);
.LBB0_76:
.LBB0_77:
	s_setprio 0
	s_add_i32 s101, s38, -2
	s_and_b32 s101, s101, 7
	s_add_i32 s101, s101, 1
	s_cmp_lt_i32 s38, 2
	s_cselect_b32 s101, 0, s101
	s_lshr_b32 s101, 0x1ce, s101
	s_and_b32 s101, s101, 1
	s_cbranch_scc0 .Lprio_skip
	v_readfirstlane_b32 s101, v222
	s_lshr_b32 s101, s101, 8
	s_cmp_eq_u32 s101, 0
	s_cbranch_scc0 .Lprio_skip
	s_setprio 1
